# C_align0 + P4: one barrier per pair of key tiles + K/V tiles brought in by direct global->LDS loads (global_load_lds_dwordx4) instead of VGPR staging + ds_write (strategy 5)
# speedup vs baseline: 1.0110x; 1.0055x over previous
; #define LAS __attribute__((address_space(3)))
; __device__ __forceinline__ void attn_unit(const Params& p, LAS unsigned char* lds, int b, int h, int qb, int tid, int wid, int lane, u64& tacc, v4u& kA, v4u& vA, v4u& kB, v4u& vB, const bool first) {
;     ...
;     const int r32 = lane & 31, hi = lane >> 5;
;     const size_t rowbase = (size_t)b * SEQ; const int q0 = qb * 256;
;     LAS bf16* stg = (LAS bf16*)(lds + 32768) + wid * 2304;
;     const bf16* Qw = proj + (rowbase + q0 + wid * 32) * NPROJ + PC_Q + h * 64;
;     bf16x8 qr[4];
; #pragma unroll
;     for (int d0 = 0; d0 < 4; ++d0) qr[d0] = *(const bf16x8*)(Qw + (size_t)r32 * NPROJ + d0 * 16 + hi * 8);
;     const int NT = 4 * (qb + 1); const int tcw = 4 * qb + (wid >> 1);
;     const bf16* ksrc = (const bf16*)((const unsigned char*)p.out + DO_KBLK) + (size_t)(b * 8 + h) * 64 * 4096 + wid * 512 + lane * 8;
;     const bf16* vsrc = (const bf16*)((const unsigned char*)p.out + DO_VBLK) + (size_t)(b * 8 + h) * 64 * 4096 + wid * 512 + lane * 8;
;     const u64* bmq = bm + (rowbase + q0 + wid * 32 + r32) * 64;
;     const unsigned stoff = wid * 1024 + lane * 16;
;     const unsigned vboff = 8192 + ((lane >> 4) & 1) * 32 + (lane & 3) * 8 + (4 * hi + ((lane & 15) >> 2)) * 64;
;     float m = 0.f; bool started = false; f32x16 o0, o1, o2;
; #pragma unroll
;     for (int i = 0; i < 16; ++i) { o0[i] = 0.f; o1[i] = 0.f; o2[i] = 0.f; }
;     float negv = -1e30f; asm volatile("" : "+v"(negv));
;     const bf16x8 ones8 = (bf16x8){0x3f80, 0x3f80, 0x3f80, 0x3f80, 0x3f80, 0x3f80, 0x3f80, 0x3f80};
;     v4u mwc = *(const v4u*)bmq, mwn = mwc;
;     if (first) {
;         kB = *(const v4u*)ksrc; vB = *(const v4u*)vsrc;
;         kA = *(const v4u*)(ksrc + (size_t)4096); vA = *(const v4u*)(vsrc + (size_t)4096);
;         *(LAS v4u*)(lds + stoff) = kB; *(LAS v4u*)(lds + 8192 + stoff) = vB;
;         kB = *(const v4u*)(ksrc + (size_t)2 * 4096); vB = *(const v4u*)(vsrc + (size_t)2 * 4096);
;     }
;     bf16x8 Eop[2];
; #pragma unroll
;     for (int s = 0; s < 2; ++s) { v4u e; unsigned* ep = (unsigned*)&e;
; #pragma unroll
;         for (int i = 0; i < 4; ++i) { const int k0 = 4 * s + i + 8 * hi; ep[i] = (r32 == k0 ? 0x3F80u : 0u) | (r32 == k0 + 16 ? 0x3F800000u : 0u); }
;         Eop[s] = __builtin_bit_cast(bf16x8, e); }
;     f32x16 nsplat;
; #pragma unroll
;     for (int r = 0; r < 16; ++r) nsplat[r] = -m;
.LBB0_3751:
	s_or_b64 exec, exec, s[0:1]
	v_readlane_b32 s0, v243, 56
	v_readlane_b32 s1, v243, 57
	s_andn2_b64 vcc, exec, s[0:1]
	s_waitcnt lgkmcnt(0)
	s_barrier
	s_cbranch_vccnz .LBB0_3772
	v_and_b32_e32 v1, 63, v167
	v_lshlrev_b32_e32 v3, 3, v167
	v_bfe_u32 v2, v167, 5, 1
	v_lshlrev_b32_e32 v158, 4, v1
	v_lshlrev_b32_e32 v1, 1, v167
	v_and_b32_e32 v3, 24, v3
	v_and_b32_e32 v156, 31, v167
	v_lshlrev_b32_e32 v160, 3, v2
	v_and_or_b32 v1, v1, 32, v3
	v_lshlrev_b32_e32 v3, 8, v2
	s_waitcnt vmcnt(2)
	v_and_b32_e32 v4, 0xc0, v158
	v_or3_b32 v157, v3, v4, v1
	v_or_b32_e32 v157, 0x8000, v157
	v_mov_b32_e32 v3, 0x3f80
	v_cmp_eq_u32_e32 vcc, v156, v160
	v_or_b32_e32 v5, 16, v160
	s_lshl_b32 s24, s84, 5
	s_lshl_b32 s75, s84, 10
	s_mov_b32 s74, 0
	v_cndmask_b32_e32 v4, 0, v3, vcc
	v_cmp_eq_u32_e32 vcc, v156, v5
	s_lshr_b32 s25, s86, 7
	s_lshl_b32 s2, s84, 10
	v_cndmask_b32_e64 v5, 0, 1.0, vcc
	v_or_b32_e32 v112, v5, v4
	v_or_b32_e32 v4, 1, v160
	v_cmp_eq_u32_e32 vcc, v156, v4
	v_or_b32_e32 v5, 17, v160
	v_readlane_b32 s0, v243, 52
	v_cndmask_b32_e32 v4, 0, v3, vcc
	v_cmp_eq_u32_e32 vcc, v156, v5
	v_readlane_b32 s1, v243, 53
	s_add_u32 s0, s0, s2
	v_cndmask_b32_e64 v5, 0, 1.0, vcc
	v_or_b32_e32 v113, v5, v4
	v_or_b32_e32 v4, 2, v160
	v_cmp_eq_u32_e32 vcc, v156, v4
	v_or_b32_e32 v5, 18, v160
	v_mov_b32_e32 v159, 0
	v_cndmask_b32_e32 v4, 0, v3, vcc
	v_cmp_eq_u32_e32 vcc, v156, v5
	s_addc_u32 s1, s1, 0
	v_readlane_b32 s4, v243, 50
	v_cndmask_b32_e64 v5, 0, 1.0, vcc
	v_or_b32_e32 v114, v5, v4
	v_or_b32_e32 v4, 3, v160
	v_cmp_eq_u32_e32 vcc, v156, v4
	v_or_b32_e32 v5, 19, v160
	v_readlane_b32 s5, v243, 51
	v_cndmask_b32_e32 v4, 0, v3, vcc
	v_cmp_eq_u32_e32 vcc, v156, v5
	s_add_u32 s4, s4, s2
	v_lshl_add_u64 v[164:165], s[0:1], 0, v[158:159]
	v_cndmask_b32_e64 v5, 0, 1.0, vcc
	v_or_b32_e32 v115, v5, v4
	v_or_b32_e32 v4, 4, v160
	v_cmp_eq_u32_e32 vcc, v156, v4
	v_or_b32_e32 v5, 20, v160
	s_mul_i32 s0, s84, 0x1200
	v_cndmask_b32_e32 v4, 0, v3, vcc
	v_cmp_eq_u32_e32 vcc, v156, v5
	s_addc_u32 s5, s5, 0
	s_add_i32 s0, s0, 0
	v_cndmask_b32_e64 v5, 0, 1.0, vcc
	v_or_b32_e32 v116, v5, v4
	v_or_b32_e32 v4, 5, v160
	v_cmp_eq_u32_e32 vcc, v156, v4
	v_or_b32_e32 v5, 21, v160
	s_movk_i32 s1, 0x90
	v_cndmask_b32_e32 v4, 0, v3, vcc
	v_cmp_eq_u32_e32 vcc, v156, v5
	v_lshl_add_u64 v[162:163], s[4:5], 0, v[158:159]
	v_or_b32_e32 v1, s2, v158
	v_cndmask_b32_e64 v5, 0, 1.0, vcc
	v_or_b32_e32 v117, v5, v4
	v_or_b32_e32 v4, 6, v160
	v_cmp_eq_u32_e32 vcc, v156, v4
	v_or_b32_e32 v5, 22, v160
	v_mov_b32_e32 v122, v159
	v_cndmask_b32_e32 v4, 0, v3, vcc
	v_cmp_eq_u32_e32 vcc, v156, v5
	v_mov_b32_e32 v123, v159
	v_mul_u32_u24_e32 v0, 0x1500, v156
	v_cndmask_b32_e64 v5, 0, 1.0, vcc
	v_or_b32_e32 v118, v5, v4
	v_or_b32_e32 v4, 7, v160
	v_cmp_eq_u32_e32 vcc, v156, v4
	v_or_b32_e32 v4, 23, v160
	v_lshl_add_u32 v5, v2, 10, 0
	v_mov_b32_e32 v2, s0
	v_cndmask_b32_e32 v3, 0, v3, vcc
	v_cmp_eq_u32_e32 vcc, v156, v4
	s_waitcnt vmcnt(1)
	v_mad_u32_u24 v9, v156, s1, v2
	v_lshlrev_b32_e32 v2, 4, v167
	v_cndmask_b32_e64 v4, 0, 1.0, vcc
	v_and_b32_e32 v158, 0x70, v2
	v_or_b32_e32 v119, v4, v3
	v_bfe_u32 v4, v167, 3, 3
	v_add_u32_e32 v10, s0, v158
	v_lshl_add_u64 v[2:3], s[82:83], 0, v[158:159]
	s_mov_b64 s[0:1], 0x1b000400
	v_lshl_add_u64 v[166:167], v[2:3], 0, s[0:1]
	v_lshlrev_b32_e32 v2, 10, v4
	v_lshlrev_b32_e32 v7, 4, v156
	v_mul_u32_u24_e32 v3, 0x90, v4
	v_or_b32_e32 v4, 0x2000, v2
	v_or_b32_e32 v6, 0x4000, v2
	v_or_b32_e32 v8, 0x6000, v2
	s_add_u32 s6, s80, 16
	v_mov_b32_e32 v120, v159
	v_mov_b32_e32 v121, v159
	v_mov_b64_e32 v[134:135], v[122:123]
	v_mov_b64_e32 v[126:127], v[122:123]
	v_mov_b64_e32 v[130:131], v[122:123]
	s_mov_b32 s3, 0
	s_addc_u32 s7, s81, 0
	v_or_b32_e32 v168, s24, v156
	v_mov_b32_e32 v169, v159
	s_mov_b64 s[12:13], 0x2000
	s_mov_b64 s[14:15], 0x4000
	v_lshlrev_b32_e32 v158, 1, v0
	v_lshlrev_b32_e32 v170, 1, v160
	s_mov_b64 s[16:17], 0x2000800
	s_brev_b32 s26, 64
	s_mov_b32 s27, 0x10001
	s_mov_b32 s28, 0x20002
	s_mov_b32 s29, 0x40004
	s_mov_b32 s30, 0x80008
	s_mov_b32 s31, 0x100010
	s_mov_b32 s33, 0x200020
	s_mov_b32 s34, 0x400040
	s_mov_b32 s35, 0x800080
	s_mov_b32 s36, 0xefa18f08
	s_mov_b32 s37, 0x41000000
	s_mov_b32 s8, 0x3f803f80
	v_add_u32_e32 v161, v9, v160
	v_add_u32_e32 v198, v10, v3
	v_add_u32_e32 v198, 0x8000, v198
	v_lshlrev_b32_e32 v172, 1, v2
	v_lshlrev_b32_e32 v174, 1, v4
	v_lshlrev_b32_e32 v176, 1, v6
	v_lshlrev_b32_e32 v178, 1, v8
	v_add_u32_e32 v199, 0, v1
	v_bfrev_b32_e32 v0, 1
	v_add_u32_e32 v200, v5, v7
	v_or_b32_e32 v200, 0x8000, v200
	v_mov_b64_e32 v[132:133], v[120:121]
	v_mov_b64_e32 v[124:125], v[120:121]
	v_mov_b64_e32 v[128:129], v[120:121]
	s_branch .LBB0_3754

; #define LAS __attribute__((address_space(3)))
; __device__ __forceinline__ void attn_unit(const Params& p, LAS unsigned char* lds, int b, int h, int qb, int tid, int wid, int lane, u64& tacc, v4u& kA, v4u& vA, v4u& kB, v4u& vB, const bool first) {
;     ...
;     const size_t rowbase = (size_t)b * SEQ; const int q0 = qb * 256;
;     LAS bf16* stg = (LAS bf16*)(lds + 32768) + wid * 2304;
;     const bf16* Qw = proj + (rowbase + q0 + wid * 32) * NPROJ + PC_Q + h * 64;
;     bf16x8 qr[4];
; #pragma unroll
;     for (int d0 = 0; d0 < 4; ++d0) qr[d0] = *(const bf16x8*)(Qw + (size_t)r32 * NPROJ + d0 * 16 + hi * 8);
;     const int NT = 4 * (qb + 1); const int tcw = 4 * qb + (wid >> 1);
;     const bf16* ksrc = (const bf16*)((const unsigned char*)p.out + DO_KBLK) + (size_t)(b * 8 + h) * 64 * 4096 + wid * 512 + lane * 8;
;     const bf16* vsrc = (const bf16*)((const unsigned char*)p.out + DO_VBLK) + (size_t)(b * 8 + h) * 64 * 4096 + wid * 512 + lane * 8;
;     const u64* bmq = bm + (rowbase + q0 + wid * 32 + r32) * 64;
;     const unsigned stoff = wid * 1024 + lane * 16;
;     const unsigned vboff = 8192 + ((lane >> 4) & 1) * 32 + (lane & 3) * 8 + (4 * hi + ((lane & 15) >> 2)) * 64;
;     float m = 0.f; bool started = false; f32x16 o0, o1, o2;
; #pragma unroll
;     for (int i = 0; i < 16; ++i) { o0[i] = 0.f; o1[i] = 0.f; o2[i] = 0.f; }
;     float negv = -1e30f; asm volatile("" : "+v"(negv));
;     const bf16x8 ones8 = (bf16x8){0x3f80, 0x3f80, 0x3f80, 0x3f80, 0x3f80, 0x3f80, 0x3f80, 0x3f80};
;     v4u mwc = *(const v4u*)bmq, mwn = mwc;
;     if (first) {
;         kB = *(const v4u*)ksrc; vB = *(const v4u*)vsrc;
;         kA = *(const v4u*)(ksrc + (size_t)4096); vA = *(const v4u*)(vsrc + (size_t)4096);
;         *(LAS v4u*)(lds + stoff) = kB; *(LAS v4u*)(lds + 8192 + stoff) = vB;
;         kB = *(const v4u*)(ksrc + (size_t)2 * 4096); vB = *(const v4u*)(vsrc + (size_t)2 * 4096);
;     }
.LBB0_3756:
	s_cmp_eq_u32 s45, 2
	s_cselect_b32 s0, s41, s42
	s_cmp_eq_u32 s45, 1
	s_cselect_b32 s0, s43, s0
	s_cmp_eq_u32 s45, 0
	s_cselect_b32 s0, s38, s0
	s_lshl_b32 s2, s0, 8
	s_add_u32 s18, s39, s2
	s_addc_u32 s19, s40, 0
	s_mul_i32 s1, s19, 0x2a00
	s_mul_hi_u32 s4, s18, 0x2a00
	s_add_i32 s4, s4, s1
	s_mul_i32 s1, s18, 0x2a00
	s_add_u32 s1, s82, s1
	s_addc_u32 s5, s83, s4
	s_add_u32 s4, s1, s44
	s_addc_u32 s5, s5, 0
	v_lshl_add_u64 v[2:3], s[4:5], 0, v[158:159]
	v_mov_b32_e32 v171, v159
	v_lshl_add_u64 v[2:3], v[2:3], 0, v[170:171]
	v_lshl_add_u64 v[4:5], v[2:3], 0, s[16:17]
	v_add_co_u32_e32 v2, vcc, s26, v2
	v_mov_b32_e32 v1, 0xf149f2ca
	s_nop 0
	v_addc_co_u32_e32 v3, vcc, 0, v3, vcc
	global_load_dwordx4 v[136:139], v[4:5], off offset:32
	global_load_dwordx4 v[140:143], v[4:5], off offset:64
	global_load_dwordx4 v[144:147], v[2:3], off offset:2048
	global_load_dwordx4 v[148:151], v[4:5], off offset:96
	v_mov_b32_e32 v3, s19
	v_or_b32_e32 v2, s18, v156
	v_lshlrev_b64 v[2:3], 9, v[2:3]
	v_lshl_add_u64 v[2:3], s[80:81], 0, v[2:3]
	global_load_dwordx4 v[152:155], v[2:3], off
	s_cmp_lg_u32 s45, 0
	s_cbranch_scc1 .LBB0_3758
	s_mov_b32 m0, s75
	s_nop 0
	global_load_lds_dwordx4 v[180:181], off
	s_add_i32 m0, s75, 0x2000
	s_nop 0
	global_load_lds_dwordx4 v[182:183], off
	s_add_i32 m0, s75, 0x4000
	s_nop 0
	global_load_lds_dwordx4 v[184:185], off
	s_add_i32 m0, s75, 0x6000
	s_nop 0
	global_load_lds_dwordx4 v[186:187], off

.LBB0_3759:
	s_add_i32 s50, s51, 2
	s_cmp_ge_u32 s50, s48
	s_cselect_b64 s[22:23], -1, 0
	v_xor_b32_e32 v200, 0x8000, v200
	v_xor_b32_e32 v157, 0x8000, v157
	s_xor_b32 s74, s74, 0x8000
	s_add_i32 s70, s74, s75
	s_waitcnt vmcnt(0) lgkmcnt(0)
	s_barrier
	s_and_b64 vcc, exec, s[22:23]
	s_cbranch_vccnz .LBB0_3761
	global_load_dwordx4 v[2:5], v[196:197], off
.LBB0_3761:
	s_add_i32 s0, s51, 2
	s_sub_i32 s1, s0, s48
	s_min_u32 s2, s0, s1
	s_lshl_b64 s[0:1], s[2:3], 13
	v_lshl_add_u64 v[6:7], v[180:181], 0, s[0:1]
	v_lshl_add_u64 v[8:9], v[182:183], 0, s[0:1]
	s_mov_b32 m0, s70
	s_nop 0
	global_load_lds_dwordx4 v[6:7], off
	s_add_i32 m0, s70, 0x2000
	s_nop 0
	global_load_lds_dwordx4 v[8:9], off
	s_add_i32 s0, s51, 3
	s_sub_i32 s1, s0, s48
	s_min_u32 s2, s0, s1
	s_lshl_b64 s[0:1], s[2:3], 13
	v_lshl_add_u64 v[6:7], v[180:181], 0, s[0:1]
	v_lshl_add_u64 v[8:9], v[182:183], 0, s[0:1]
	s_add_i32 m0, s70, 0x4000
	s_nop 0
	global_load_lds_dwordx4 v[6:7], off
	s_add_i32 m0, s70, 0x6000
	s_nop 0
	global_load_lds_dwordx4 v[8:9], off
	s_cmp_gt_u32 s51, s47
	s_cbranch_scc1 .LBB0_3765
	ds_read_b128 v[6:9], v200
	ds_read_b128 v[10:13], v200 offset:512
	v_lshrrev_b32_e32 v1, v160, v152
	v_lshrrev_b32_e32 v14, v160, v153
	v_bitop3_b32 v228, v1, s27, v1 bitop3:0xc
	v_bitop3_b32 v229, v1, s28, v1 bitop3:0xc
	v_bitop3_b32 v230, v1, s29, v1 bitop3:0xc
	v_bitop3_b32 v231, v1, s30, v1 bitop3:0xc
	s_waitcnt lgkmcnt(1)
	v_mfma_f32_32x32x16_bf16 v[80:95], v[6:9], v[144:147], v[64:79]
	v_mul_u32_u24_e32 v228, 0xf000, v228
	v_mul_u32_u24_e32 v229, 0x7800, v229
	v_mul_u32_u24_e32 v230, 0x3c00, v230
	v_mul_u32_u24_e32 v231, 0x1e00, v231
	s_waitcnt lgkmcnt(0)
	v_mfma_f32_32x32x16_bf16 v[96:111], v[10:13], v[144:147], v[64:79]
	ds_read_b128 v[6:9], v200 offset:2048
	ds_read_b128 v[10:13], v200 offset:2560
	v_bitop3_b32 v232, v14, s27, v14 bitop3:0xc
	v_bitop3_b32 v233, v14, s28, v14 bitop3:0xc
	v_bitop3_b32 v234, v14, s29, v14 bitop3:0xc
	v_bitop3_b32 v235, v14, s30, v14 bitop3:0xc
	v_mul_u32_u24_e32 v232, 0xf000, v232
	v_mul_u32_u24_e32 v233, 0x7800, v233
	v_mul_u32_u24_e32 v234, 0x3c00, v234
	v_mul_u32_u24_e32 v235, 0x1e00, v235
	s_waitcnt lgkmcnt(1)
	v_mfma_f32_32x32x16_bf16 v[80:95], v[6:9], v[136:139], v[80:95]
	v_bitop3_b32 v236, v1, s31, v1 bitop3:0xc
	v_bitop3_b32 v237, v1, s33, v1 bitop3:0xc
	v_bitop3_b32 v238, v1, s34, v1 bitop3:0xc
	v_bitop3_b32 v239, v1, s35, v1 bitop3:0xc
	s_waitcnt lgkmcnt(0)
	v_mfma_f32_32x32x16_bf16 v[96:111], v[10:13], v[136:139], v[96:111]
	ds_read_b128 v[6:9], v200 offset:4096
	ds_read_b128 v[10:13], v200 offset:4608
	v_mul_u32_u24_e32 v236, 0xf00, v236
	v_mul_u32_u24_e32 v237, 0x780, v237
	v_mul_u32_u24_e32 v238, 0x3c0, v238
	v_mul_u32_u24_e32 v239, 0x1e0, v239
	v_bitop3_b32 v224, v14, s31, v14 bitop3:0xc
	v_bitop3_b32 v225, v14, s33, v14 bitop3:0xc
	v_bitop3_b32 v226, v14, s34, v14 bitop3:0xc
	v_bitop3_b32 v227, v14, s35, v14 bitop3:0xc
	s_waitcnt lgkmcnt(1)
	v_mfma_f32_32x32x16_bf16 v[80:95], v[6:9], v[140:143], v[80:95]
	v_mul_u32_u24_e32 v224, 0xf00, v224
	v_mul_u32_u24_e32 v225, 0x780, v225
	v_mul_u32_u24_e32 v226, 0x3c0, v226
	v_mul_u32_u24_e32 v227, 0x1e0, v227
	s_waitcnt lgkmcnt(0)
	v_mfma_f32_32x32x16_bf16 v[96:111], v[10:13], v[140:143], v[96:111]
	ds_read_b128 v[6:9], v200 offset:6144
	ds_read_b128 v[10:13], v200 offset:6656
	s_xor_b64 s[4:5], s[20:21], -1
	s_waitcnt lgkmcnt(1)
	v_mfma_f32_32x32x16_bf16 v[80:95], v[6:9], v[148:151], v[80:95]
	s_waitcnt lgkmcnt(0)
	v_mfma_f32_32x32x16_bf16 v[96:111], v[10:13], v[148:151], v[96:111]
	v_mfma_f32_32x32x16_bf16 v[80:95], v[112:115], v[228:231], v[80:95]
	v_mfma_f32_32x32x16_bf16 v[96:111], v[112:115], v[232:235], v[96:111]
	v_mfma_f32_32x32x16_bf16 v[80:95], v[116:119], v[236:239], v[80:95]
	v_mfma_f32_32x32x16_bf16 v[96:111], v[116:119], v[224:227], v[96:111]
	s_nop 15
	s_nop 7
	v_max3_f32 v1, v80, v81, v82
	v_max3_f32 v6, v83, v84, v85
	v_max3_f32 v1, v1, v86, v87
	v_max3_f32 v6, v6, v88, v89
	v_max3_f32 v1, v1, v90, v91
	v_max3_f32 v6, v6, v92, v93
	v_max3_f32 v1, v1, v94, v95
	v_max_f32 v1, v1, v6
	s_nop 0
	v_max3_f32 v7, v96, v97, v98
	v_max3_f32 v6, v99, v100, v101
	v_max3_f32 v7, v7, v102, v103
	v_max3_f32 v6, v6, v104, v105
	v_max3_f32 v7, v7, v106, v107
	v_max3_f32 v6, v6, v108, v109
	v_max3_f32 v7, v7, v110, v111
	v_max3_f32 v7, v7, v6, v1
	s_nop 0
	v_mov_b32_e32 v1, v7
	s_nop 1
	v_permlane32_swap_b32_e32 v7, v1
	v_max_f32_e32 v1, v1, v1
	v_max_f32_e32 v6, v7, v7
	v_max_f32_e32 v1, v6, v1
	v_cmp_lt_f32_e64 s[0:1], s36, v1
	s_and_b64 s[10:11], s[0:1], s[4:5]
	v_cmp_lt_f32_e32 vcc, s37, v1
	s_or_b64 s[4:5], vcc, s[10:11]
	v_cndmask_b32_e64 v6, 0, 1, s[4:5]
	v_cmp_ne_u32_e32 vcc, 0, v6
	s_cbranch_vccz .LBB0_3764
	v_cndmask_b32_e64 v6, 0, v1, s[4:5]
	v_exp_f32_e64 v1, -v6
	v_add_f32_e32 v171, v171, v6
	s_or_b64 s[0:1], s[20:21], s[0:1]
	v_xor_b32_e32 v64, 0x80000000, v171
	v_cndmask_b32_e64 v8, v1, 1.0, s[10:11]
	s_andn2_b64 s[4:5], s[20:21], exec
	s_and_b64 s[0:1], s[0:1], exec
	v_pk_add_f32 v[80:81], v[80:81], v[6:7] op_sel_hi:[1,0] neg_lo:[0,1] neg_hi:[0,1]
	v_pk_add_f32 v[96:97], v[96:97], v[6:7] op_sel_hi:[1,0] neg_lo:[0,1] neg_hi:[0,1]
	v_pk_add_f32 v[82:83], v[82:83], v[6:7] op_sel_hi:[1,0] neg_lo:[0,1] neg_hi:[0,1]
	v_pk_add_f32 v[98:99], v[98:99], v[6:7] op_sel_hi:[1,0] neg_lo:[0,1] neg_hi:[0,1]
	v_pk_add_f32 v[84:85], v[84:85], v[6:7] op_sel_hi:[1,0] neg_lo:[0,1] neg_hi:[0,1]
	v_pk_add_f32 v[100:101], v[100:101], v[6:7] op_sel_hi:[1,0] neg_lo:[0,1] neg_hi:[0,1]
	v_pk_add_f32 v[86:87], v[86:87], v[6:7] op_sel_hi:[1,0] neg_lo:[0,1] neg_hi:[0,1]
	v_pk_add_f32 v[102:103], v[102:103], v[6:7] op_sel_hi:[1,0] neg_lo:[0,1] neg_hi:[0,1]
	v_pk_add_f32 v[88:89], v[88:89], v[6:7] op_sel_hi:[1,0] neg_lo:[0,1] neg_hi:[0,1]
	v_pk_add_f32 v[104:105], v[104:105], v[6:7] op_sel_hi:[1,0] neg_lo:[0,1] neg_hi:[0,1]
	v_pk_add_f32 v[90:91], v[90:91], v[6:7] op_sel_hi:[1,0] neg_lo:[0,1] neg_hi:[0,1]
	v_pk_add_f32 v[106:107], v[106:107], v[6:7] op_sel_hi:[1,0] neg_lo:[0,1] neg_hi:[0,1]
	v_pk_add_f32 v[92:93], v[92:93], v[6:7] op_sel_hi:[1,0] neg_lo:[0,1] neg_hi:[0,1]
	v_pk_add_f32 v[108:109], v[108:109], v[6:7] op_sel_hi:[1,0] neg_lo:[0,1] neg_hi:[0,1]
	v_pk_add_f32 v[94:95], v[94:95], v[6:7] op_sel_hi:[1,0] neg_lo:[0,1] neg_hi:[0,1]
	v_pk_add_f32 v[110:111], v[110:111], v[6:7] op_sel_hi:[1,0] neg_lo:[0,1] neg_hi:[0,1]
	v_mov_b32_e32 v65, v64
	v_mov_b32_e32 v66, v64
	v_mov_b32_e32 v67, v64
	v_mov_b32_e32 v68, v64
	v_mov_b32_e32 v69, v64
	v_mov_b32_e32 v70, v64
	v_mov_b32_e32 v71, v64
	v_mov_b32_e32 v72, v64
	v_mov_b32_e32 v73, v64
	v_mov_b32_e32 v74, v64
	v_mov_b32_e32 v75, v64
	v_mov_b32_e32 v76, v64
	v_mov_b32_e32 v77, v64
	v_mov_b32_e32 v78, v64
	v_mov_b32_e32 v79, v64
	v_pk_mul_f32 v[30:31], v[30:31], v[8:9] op_sel_hi:[1,0]
	v_pk_mul_f32 v[28:29], v[28:29], v[8:9] op_sel_hi:[1,0]
	v_pk_mul_f32 v[26:27], v[26:27], v[8:9] op_sel_hi:[1,0]
	v_pk_mul_f32 v[24:25], v[24:25], v[8:9] op_sel_hi:[1,0]
	v_pk_mul_f32 v[22:23], v[22:23], v[8:9] op_sel_hi:[1,0]
	v_pk_mul_f32 v[20:21], v[20:21], v[8:9] op_sel_hi:[1,0]
	v_pk_mul_f32 v[18:19], v[18:19], v[8:9] op_sel_hi:[1,0]
	v_pk_mul_f32 v[16:17], v[16:17], v[8:9] op_sel_hi:[1,0]
	v_pk_mul_f32 v[46:47], v[46:47], v[8:9] op_sel_hi:[1,0]
	v_pk_mul_f32 v[44:45], v[44:45], v[8:9] op_sel_hi:[1,0]
	v_pk_mul_f32 v[42:43], v[42:43], v[8:9] op_sel_hi:[1,0]
	v_pk_mul_f32 v[40:41], v[40:41], v[8:9] op_sel_hi:[1,0]
	v_pk_mul_f32 v[38:39], v[38:39], v[8:9] op_sel_hi:[1,0]
	v_pk_mul_f32 v[36:37], v[36:37], v[8:9] op_sel_hi:[1,0]
	v_pk_mul_f32 v[34:35], v[34:35], v[8:9] op_sel_hi:[1,0]
	v_pk_mul_f32 v[32:33], v[32:33], v[8:9] op_sel_hi:[1,0]
	v_pk_mul_f32 v[62:63], v[62:63], v[8:9] op_sel_hi:[1,0]
	v_pk_mul_f32 v[60:61], v[60:61], v[8:9] op_sel_hi:[1,0]
	v_pk_mul_f32 v[58:59], v[58:59], v[8:9] op_sel_hi:[1,0]
	v_pk_mul_f32 v[56:57], v[56:57], v[8:9] op_sel_hi:[1,0]
	v_pk_mul_f32 v[54:55], v[54:55], v[8:9] op_sel_hi:[1,0]
	v_pk_mul_f32 v[52:53], v[52:53], v[8:9] op_sel_hi:[1,0]
	v_pk_mul_f32 v[50:51], v[50:51], v[8:9] op_sel_hi:[1,0]
	v_pk_mul_f32 v[48:49], v[48:49], v[8:9] op_sel_hi:[1,0]
	s_or_b64 s[20:21], s[4:5], s[0:1]

;     __device__ bool next(int i, Unit& u) const { if (i != 0) return false; return so.next(round, u); }
;     __device__ __forceinline__ bool next(int i, Unit& u) const { if (i > 0 || !on) return false; u.pm = pm; u.pn = 0; return true; }
; template <class Epi, class Sched, bool ALIGN_EPI = false, bool SP2 = false, bool MIDHOOK = false>
; __device__ __forceinline__ void gemm_phase(PG8_LAS unsigned char* lds, const Gemm g, const Sched& S, const Epi& E) {
;     ...
;         const bool has_next = S.next(ui + 1, nxt);
;         const char* nA = has_next ? (const char*)g.A + (size_t)nxt.pm * tstep : cA; const char* nB = has_next ? (const char*)g.Bt + (size_t)nxt.pn * tstep : cB;
;         for (int t = 0; t < nt; t += 2) {
;             if constexpr (MIDHOOK) { if (t == nt / 2) E.mid(acc, cur, wr, wc, fr, fq); }
;             const bool last = (t == nt - 2);
;             const char* a1 = cA + (size_t)(t + 1) * kstep;
;             const char* a2 = last ? nA : cA + (size_t)(t + 2) * kstep; const char* b2 = last ? nB : cB + (size_t)(t + 2) * kstep;
;     ...
; #pragma unroll
;         for (int a = 0; a < 2; ++a)
; #pragma unroll
;             for (int b = 0; b < 2; ++b)
; #pragma unroll
;                 for (int m = 0; m < 4; ++m)
; #pragma unroll
;                     for (int n = 0; n < 2; ++n) acc[a][b][m][n] = (f32x4){0.f, 0.f, 0.f, 0.f};
;         cur = nxt; cA = nA; cB = nB; ++ui;
.LBB0_3840:
	s_ashr_i32 s19, s18, 31
	s_lshl_b64 s[20:21], s[18:19], 19
	s_add_u32 s20, s68, s20
	s_addc_u32 s21, s69, s21
	s_and_b64 s[22:23], s[0:1], exec
	s_cselect_b32 s19, s21, s25
	s_cselect_b32 s46, s20, s24
	s_ashr_i32 s17, s16, 31
	s_lshl_b64 s[22:23], s[16:17], 19
	v_readlane_b32 s30, v243, 24
	v_readlane_b32 s31, v243, 25
	s_add_u32 s22, s30, s22
	s_addc_u32 s23, s31, s23
	s_and_b64 s[30:31], s[0:1], exec
	v_mov_b32_e32 v2, v0
	v_mov_b32_e32 v3, v0
	s_cselect_b32 s17, s23, s29
	s_cselect_b32 s47, s22, s28
	s_add_u32 s48, s28, 0x100
	v_mov_b32_e32 v1, v0
	v_mov_b64_e32 v[6:7], v[2:3]
	v_mov_b64_e32 v[10:11], v[2:3]
	v_mov_b64_e32 v[22:23], v[2:3]
	v_mov_b64_e32 v[26:27], v[2:3]
	v_mov_b64_e32 v[38:39], v[2:3]
	v_mov_b64_e32 v[42:43], v[2:3]
	v_mov_b64_e32 v[54:55], v[2:3]
	v_mov_b64_e32 v[58:59], v[2:3]
	v_mov_b64_e32 v[14:15], v[2:3]
	v_mov_b64_e32 v[18:19], v[2:3]
	v_mov_b64_e32 v[30:31], v[2:3]
	v_mov_b64_e32 v[34:35], v[2:3]
	v_mov_b64_e32 v[46:47], v[2:3]
	v_mov_b64_e32 v[50:51], v[2:3]
	v_mov_b64_e32 v[62:63], v[2:3]
	v_mov_b64_e32 v[66:67], v[2:3]
	v_mov_b64_e32 v[70:71], v[2:3]
	v_mov_b64_e32 v[74:75], v[2:3]
	v_mov_b64_e32 v[86:87], v[2:3]
	v_mov_b64_e32 v[90:91], v[2:3]
	v_mov_b64_e32 v[102:103], v[2:3]
	v_mov_b64_e32 v[106:107], v[2:3]
	v_mov_b64_e32 v[118:119], v[2:3]
	v_mov_b64_e32 v[122:123], v[2:3]
	v_mov_b64_e32 v[78:79], v[2:3]
	v_mov_b64_e32 v[82:83], v[2:3]
	v_mov_b64_e32 v[94:95], v[2:3]
	v_mov_b64_e32 v[98:99], v[2:3]
	v_mov_b64_e32 v[110:111], v[2:3]
	v_mov_b64_e32 v[114:115], v[2:3]
	v_mov_b64_e32 v[126:127], v[2:3]
	v_mov_b64_e32 v[130:131], v[2:3]
	v_lshl_add_u32 v204, s26, 8, v223
	v_lshl_add_u32 v206, s27, 8, v225
	v_lshl_add_u64 v[208:209], s[24:25], 0, v[196:197]
	v_lshl_add_u64 v[210:211], s[24:25], 0, v[198:199]
	s_addc_u32 s49, s29, 0
	s_mov_b32 s50, -2
	s_mov_b64 s[26:27], 0
	v_mov_b64_e32 v[4:5], v[0:1]
	v_mov_b64_e32 v[8:9], v[0:1]
	v_mov_b64_e32 v[20:21], v[0:1]
	v_mov_b64_e32 v[24:25], v[0:1]
	v_mov_b64_e32 v[36:37], v[0:1]
	v_mov_b64_e32 v[40:41], v[0:1]
	v_mov_b64_e32 v[52:53], v[0:1]
	v_mov_b64_e32 v[56:57], v[0:1]
	v_mov_b64_e32 v[12:13], v[0:1]
	v_mov_b64_e32 v[16:17], v[0:1]
	v_mov_b64_e32 v[28:29], v[0:1]
	v_mov_b64_e32 v[32:33], v[0:1]
	v_mov_b64_e32 v[44:45], v[0:1]
	v_mov_b64_e32 v[48:49], v[0:1]
	v_mov_b64_e32 v[60:61], v[0:1]
	v_mov_b64_e32 v[64:65], v[0:1]
	v_mov_b64_e32 v[68:69], v[0:1]
	v_mov_b64_e32 v[72:73], v[0:1]
	v_mov_b64_e32 v[84:85], v[0:1]
	v_mov_b64_e32 v[88:89], v[0:1]
	v_mov_b64_e32 v[100:101], v[0:1]
	v_mov_b64_e32 v[104:105], v[0:1]
	v_mov_b64_e32 v[116:117], v[0:1]
	v_mov_b64_e32 v[120:121], v[0:1]
	v_mov_b64_e32 v[76:77], v[0:1]
	v_mov_b64_e32 v[80:81], v[0:1]
	v_mov_b64_e32 v[92:93], v[0:1]
	v_mov_b64_e32 v[96:97], v[0:1]
	v_mov_b64_e32 v[108:109], v[0:1]
	v_mov_b64_e32 v[112:113], v[0:1]
	v_mov_b64_e32 v[124:125], v[0:1]
	v_mov_b64_e32 v[128:129], v[0:1]
	s_branch .LBB0_3842
	s_nop 0
	s_nop 0
	s_nop 0
	s_nop 0
	s_nop 0
	s_nop 0
	s_nop 0
	s_nop 0
	s_nop 0
	s_nop 0
